# v25: v22 + P2 hgrn_item pass 1 packs of the prefetched sub-chunk deferred to the end of the iteration
# speedup vs baseline: 1.0044x; 1.0044x over previous
; template <bool OUT> DI void hgrn_item(LAS unsigned char* lds, bf16_t* proj, float* hst, float* hdv, const float* normw, int item, bool dry) {
;     ...
;         if (sc < 3) HG_LOAD(sc + 1);
.LBB0_826:
	v_lshl_add_u64 v[34:35], v[56:57], 0, s[36:37]
	v_add_co_u32_e32 v36, vcc, 0xc8000, v34
	s_nop 1
	v_addc_co_u32_e32 v37, vcc, 0, v35, vcc
	v_add_co_u32_e32 v38, vcc, 0xcb000, v34
	s_nop 1
	v_addc_co_u32_e32 v39, vcc, 0, v35, vcc
	v_add_co_u32_e32 v40, vcc, 0xcc000, v34
	s_nop 1
	v_addc_co_u32_e32 v41, vcc, 0, v35, vcc
	v_add_co_u32_e32 v72, vcc, 0xce000, v34
	s_nop 1
	v_addc_co_u32_e32 v73, vcc, 0, v35, vcc
	v_add_co_u32_e32 v74, vcc, 0xd2000, v34
	s_nop 1
	v_addc_co_u32_e32 v75, vcc, 0, v35, vcc
	v_add_co_u32_e32 v76, vcc, 0xcf000, v34
	s_nop 1
	v_addc_co_u32_e32 v77, vcc, 0, v35, vcc
	global_load_ushort v130, v[36:37], off offset:2560
	global_load_ushort v131, v[38:39], off offset:3072
	global_load_ushort v132, v[40:41], off
	global_load_ushort v133, v[72:73], off offset:3584
	global_load_ushort v134, v[74:75], off
	global_load_ushort v135, v[76:77], off offset:512
	global_load_ushort v136, v[74:75], off offset:1024
	global_load_ushort v137, v[36:37], off offset:3584
	v_add_co_u32_e32 v36, vcc, 0xd5000, v34
	s_nop 1
	v_addc_co_u32_e32 v37, vcc, 0, v35, vcc
	v_add_co_u32_e32 v38, vcc, 0xd8000, v34
	s_nop 1
	v_addc_co_u32_e32 v39, vcc, 0, v35, vcc
	v_add_co_u32_e32 v40, vcc, 0xdb000, v34
	s_nop 1
	v_addc_co_u32_e32 v41, vcc, 0, v35, vcc
	v_add_co_u32_e32 v72, vcc, 0xde000, v34
	s_nop 1
	v_addc_co_u32_e32 v73, vcc, 0, v35, vcc
	global_load_ushort v138, v[36:37], off offset:512
	global_load_ushort v139, v[38:39], off offset:1024
	global_load_ushort v140, v[38:39], off offset:2048
	global_load_ushort v141, v[40:41], off offset:1536
	global_load_ushort v142, v[72:73], off offset:2048
	global_load_ushort v143, v[72:73], off offset:3072
	global_load_ushort v144, v[40:41], off offset:2560
	global_load_ushort v145, v[36:37], off offset:1536
	v_add_co_u32_e32 v36, vcc, 0xe1000, v34
	s_nop 1
	v_addc_co_u32_e32 v37, vcc, 0, v35, vcc
	v_add_co_u32_e32 v38, vcc, 0xe4000, v34
	s_nop 1
	v_addc_co_u32_e32 v39, vcc, 0, v35, vcc
	v_add_co_u32_e32 v40, vcc, 0xe5000, v34
	s_nop 1
	v_addc_co_u32_e32 v41, vcc, 0, v35, vcc
	v_add_co_u32_e32 v72, vcc, 0xe7000, v34
	s_nop 1
	v_addc_co_u32_e32 v73, vcc, 0, v35, vcc
	v_add_co_u32_e32 v74, vcc, 0xeb000, v34
	s_nop 1
	v_addc_co_u32_e32 v75, vcc, 0, v35, vcc
	v_add_co_u32_e32 v76, vcc, 0xe8000, v34
	s_nop 1
	v_addc_co_u32_e32 v77, vcc, 0, v35, vcc
	global_load_ushort v146, v[36:37], off offset:2560
	global_load_ushort v147, v[38:39], off offset:3072
	global_load_ushort v148, v[40:41], off
	global_load_ushort v149, v[72:73], off offset:3584
	global_load_ushort v150, v[74:75], off
	global_load_ushort v151, v[76:77], off offset:512
	global_load_ushort v152, v[74:75], off offset:1024
	s_nop 0
	global_load_ushort v153, v[36:37], off offset:3584
	v_add_co_u32_e32 v36, vcc, 0xee000, v34
	v_addc_co_u32_e32 v37, vcc, 0, v35, vcc
	v_add_co_u32_e32 v38, vcc, 0xf1000, v34
	v_addc_co_u32_e32 v39, vcc, 0, v35, vcc
	v_add_co_u32_e32 v40, vcc, 0xf4000, v34
	v_addc_co_u32_e32 v41, vcc, 0, v35, vcc
	v_add_co_u32_e32 v34, vcc, 0xf7000, v34
	v_addc_co_u32_e32 v35, vcc, 0, v35, vcc
	global_load_ushort v154, v[36:37], off offset:512
	global_load_ushort v155, v[38:39], off offset:1024
	global_load_ushort v156, v[38:39], off offset:2048
	global_load_ushort v157, v[40:41], off offset:1536
	global_load_ushort v158, v[34:35], off offset:3072
	s_nop 0
	global_load_ushort v159, v[40:41], off offset:2560
	s_nop 0
	global_load_ushort v160, v[36:37], off offset:1536
	global_load_ushort v161, v[34:35], off offset:2048

; #define LAS __attribute__((address_space(3)))
; DI unsigned pk2(float lo, float hi) { f32x2 v = {lo, hi}; bfv2 b = __builtin_convertvector(v, bfv2); return __builtin_bit_cast(unsigned, b); }
; DI bf16_t f2bf(float x) { return (bf16_t)(pk2(x, 0.f) & 0xffffu); }
; DI float fexp(float x) { return __builtin_amdgcn_exp2f(x * LOG2E); }
; template <bool OUT> DI void hgrn_item(LAS unsigned char* lds, bf16_t* proj, float* hst, float* hdv, const float* normw, int item, bool dry) {
;     ...
;         float off = 0.f, tot = 0.f;
; #pragma unroll
;         for (int q = 0; q < 4; ++q) { const float p = bpart[q * 128 + d]; tot += p; if (q < tq) off += p; }
;         btot += tot;
;         if (tq == 0) Dv[d] = fexp(tot);
;         {
;             unsigned kk[8];
; #pragma unroll
;             for (int i = 0; i < 8; ++i) {
;                 const float b0 = off + bl[2 * i], b1 = off + bl[2 * i + 1];
;                 const float k0 = (1.0f - fexp(gl[2 * i])) * fexp(-b0), k1 = (1.0f - fexp(gl[2 * i + 1])) * fexp(-b1);
;                 kk[i] = pk2(k0, k1);
;                 if (OUT) { Kt[(tq * 16 + 2 * i) * QP + d] = (bf16_t)(kk[i] & 0xffffu); Kt[(tq * 16 + 2 * i + 1) * QP + d] = (bf16_t)(kk[i] >> 16);
;                     Qt[(tq * 16 + 2 * i) * QP + d] = f2bf(qv[2 * i] * fexp(b0)); Qt[(tq * 16 + 2 * i + 1) * QP + d] = f2bf(qv[2 * i + 1] * fexp(b1)); }
;             }
;             *(LAS u32x4*)(KtT + d * TP + tq * 16) = (u32x4){kk[0], kk[1], kk[2], kk[3]};
;             *(LAS u32x4*)(KtT + d * TP + tq * 16 + 8) = (u32x4){kk[4], kk[5], kk[6], kk[7]};
;         }
;         __syncthreads();
.LBB0_829:
	s_or_b64 exec, exec, s[38:39]
	v_cndmask_b32_e64 v112, v112, 0, s[4:5]
	v_add_f32_e32 v61, v61, v112
	v_cndmask_b32_e64 v61, v112, v61, s[6:7]
	v_add_f32_e32 v58, v58, v61
	v_cndmask_b32_e64 v58, v61, v58, s[8:9]
	v_add_f32_e32 v59, v59, v58
	v_cndmask_b32_e64 v61, v58, v59, s[10:11]
	v_add_f32_e32 v59, v110, v61
	v_add_f32_e32 v110, v111, v61
	v_mul_f32_e32 v58, 0x3fb8aa3b, v107
	v_mul_f32_e32 v107, 0xbfb8aa3b, v59
	v_mul_f32_e32 v59, 0x3fb8aa3b, v106
	v_exp_f32_e32 v58, v58
	v_exp_f32_e32 v59, v59
	v_exp_f32_e32 v106, v107
	v_mul_f32_e32 v107, 0xbfb8aa3b, v110
	v_exp_f32_e32 v107, v107
	v_add_f32_e32 v110, v108, v61
	v_add_f32_e32 v111, v109, v61
	v_mul_f32_e32 v103, 0x3fb8aa3b, v103
	v_mul_f32_e32 v102, 0x3fb8aa3b, v102
	v_exp_f32_e32 v108, v103
	v_mul_f32_e32 v103, 0xbfb8aa3b, v110
	v_exp_f32_e32 v109, v102
	v_mul_f32_e32 v102, 0xbfb8aa3b, v111
	v_exp_f32_e32 v110, v103
	v_exp_f32_e32 v111, v102
	v_pk_add_f32 v[58:59], v[58:59], 1.0 op_sel_hi:[1,0] neg_lo:[1,0] neg_hi:[1,0]
	v_mul_f32_e32 v97, 0x3fb8aa3b, v97
	v_pk_mul_f32 v[58:59], v[58:59], v[106:107]
	v_mul_f32_e32 v94, 0x3fb8aa3b, v94
	v_cvt_pk_bf16_f32 v102, v58, v59
	v_pk_add_f32 v[58:59], v[108:109], 1.0 op_sel_hi:[1,0] neg_lo:[1,0] neg_hi:[1,0]
	v_mul_f32_e32 v87, 0x3fb8aa3b, v87
	v_pk_mul_f32 v[58:59], v[58:59], v[110:111]
	v_mul_f32_e32 v86, 0x3fb8aa3b, v86
	v_cvt_pk_bf16_f32 v103, v58, v59
	v_add_f32_e32 v59, v104, v61
	v_add_f32_e32 v104, v105, v61
	v_mul_f32_e32 v58, 0x3fb8aa3b, v99
	v_mul_f32_e32 v99, 0xbfb8aa3b, v59
	v_mul_f32_e32 v59, 0x3fb8aa3b, v98
	v_exp_f32_e32 v58, v58
	v_exp_f32_e32 v59, v59
	v_exp_f32_e32 v98, v99
	v_mul_f32_e32 v99, 0xbfb8aa3b, v104
	v_exp_f32_e32 v99, v99
	v_add_f32_e32 v104, v100, v61
	v_add_f32_e32 v105, v101, v61
	v_exp_f32_e32 v100, v97
	v_mul_f32_e32 v97, 0xbfb8aa3b, v104
	v_exp_f32_e32 v101, v94
	v_mul_f32_e32 v94, 0xbfb8aa3b, v105
	v_exp_f32_e32 v106, v97
	v_exp_f32_e32 v107, v94
	v_pk_add_f32 v[58:59], v[58:59], 1.0 op_sel_hi:[1,0] neg_lo:[1,0] neg_hi:[1,0]
	v_add_f32_e32 v94, v96, v61
	v_pk_mul_f32 v[58:59], v[58:59], v[98:99]
	v_add_f32_e32 v89, v89, v61
	v_cvt_pk_bf16_f32 v104, v58, v59
	v_pk_add_f32 v[58:59], v[100:101], 1.0 op_sel_hi:[1,0] neg_lo:[1,0] neg_hi:[1,0]
	v_add_f32_e32 v83, v83, v61
	v_pk_mul_f32 v[58:59], v[58:59], v[106:107]
	v_mul_f32_e32 v81, 0x3fb8aa3b, v81
	v_cvt_pk_bf16_f32 v105, v58, v59
	v_add_f32_e32 v59, v95, v61
	v_mul_f32_e32 v58, 0x3fb8aa3b, v91
	v_mul_f32_e32 v91, 0xbfb8aa3b, v59
	v_mul_f32_e32 v59, 0x3fb8aa3b, v90
	v_exp_f32_e32 v58, v58
	v_exp_f32_e32 v59, v59
	v_exp_f32_e32 v90, v91
	v_mul_f32_e32 v91, 0xbfb8aa3b, v94
	v_exp_f32_e32 v91, v91
	v_add_f32_e32 v94, v92, v61
	v_add_f32_e32 v95, v93, v61
	v_exp_f32_e32 v92, v87
	v_mul_f32_e32 v87, 0xbfb8aa3b, v94
	v_exp_f32_e32 v93, v86
	v_mul_f32_e32 v86, 0xbfb8aa3b, v95
	v_exp_f32_e32 v94, v87
	v_exp_f32_e32 v95, v86
	v_pk_add_f32 v[58:59], v[58:59], 1.0 op_sel_hi:[1,0] neg_lo:[1,0] neg_hi:[1,0]
	v_mul_f32_e32 v80, 0x3fb8aa3b, v80
	v_pk_mul_f32 v[58:59], v[58:59], v[90:91]
	v_add_f32_e32 v70, v70, v60
	v_cvt_pk_bf16_f32 v86, v58, v59
	v_pk_add_f32 v[58:59], v[92:93], 1.0 op_sel_hi:[1,0] neg_lo:[1,0] neg_hi:[1,0]
	s_add_u32 s36, s36, 0xc8000
	v_pk_mul_f32 v[58:59], v[58:59], v[94:95]
	s_addc_u32 s37, s37, 0
	v_cvt_pk_bf16_f32 v87, v58, v59
	v_add_f32_e32 v59, v88, v61
	v_mul_f32_e32 v58, 0x3fb8aa3b, v84
	v_mul_f32_e32 v84, 0xbfb8aa3b, v59
	v_mul_f32_e32 v59, 0x3fb8aa3b, v82
	v_exp_f32_e32 v58, v58
	v_exp_f32_e32 v59, v59
	v_mul_f32_e32 v82, 0xbfb8aa3b, v89
	v_exp_f32_e32 v88, v84
	v_exp_f32_e32 v89, v82
	v_add_f32_e32 v61, v85, v61
	v_exp_f32_e32 v82, v81
	v_mul_f32_e32 v81, 0xbfb8aa3b, v83
	v_exp_f32_e32 v83, v80
	v_mul_f32_e32 v61, 0xbfb8aa3b, v61
	v_exp_f32_e32 v84, v81
	v_exp_f32_e32 v85, v61
	v_pk_add_f32 v[58:59], v[58:59], 1.0 op_sel_hi:[1,0] neg_lo:[1,0] neg_hi:[1,0]
	s_cmp_eq_u32 s36, 0x320000
	v_pk_mul_f32 v[58:59], v[58:59], v[88:89]
	s_nop 0
	v_cvt_pk_bf16_f32 v88, v58, v59
	v_pk_add_f32 v[58:59], v[82:83], 1.0 op_sel_hi:[1,0] neg_lo:[1,0] neg_hi:[1,0]
	s_nop 0
	v_pk_mul_f32 v[58:59], v[58:59], v[84:85]
	s_nop 0
	v_cvt_pk_bf16_f32 v89, v58, v59
	ds_write_b128 v63, v[102:105] offset:34816
	ds_write_b128 v63, v[86:89] offset:34832
	s_waitcnt lgkmcnt(0)
	s_barrier
; #define LAS __attribute__((address_space(3)))
; DI bf16_t f2bf(float x) { return (bf16_t)(pk2(x, 0.f) & 0xffffu); }
; template <bool OUT> DI void hgrn_item(LAS unsigned char* lds, bf16_t* proj, float* hst, float* hdv, const float* normw, int item, bool dry) {
;     ...
;     HG_LOAD(0);
; #pragma unroll 1
;     for (int sc = 0; sc < 4; ++sc) {
;         const size_t row0 = (size_t)b * 4096 + c * 256 + sc * 64;
;         float gl[16], qv[16];
; #pragma unroll
;     ...
;         for (int ks = 0; ks < 2; ++ks) vfr[ks] = *(const LAS bf16x8*)(VT + (w * 16 + e16) * TP + 32 * ks + 8 * rq);
;         if (OUT) {
; #pragma unroll
;             for (int u = 0; u < 2; ++u) { const int id = w + 8 * u, ti = id >> 2, sj = id & 3;
;                 f32x4 a = {0.f, 0.f, 0.f, 0.f};
;                 if (sj <= ti) {
; #pragma unroll
;                     for (int ks = 0; ks < 4; ++ks) { const bf16x8 qa = *(const LAS bf16x8*)(Qt + (16 * ti + e16) * QP + 32 * ks + 8 * rq), kb = *(const LAS bf16x8*)(Kt + (16 * sj + e16) * QP + 32 * ks + 8 * rq);
;                         a = MFMA16(qa, kb, a); }
;                 }
; #pragma unroll
;                 for (int r = 0; r < 4; ++r) { const int tt = 16 * ti + 4 * rq + r, ss = 16 * sj + e16; Ab[tt * TP + ss] = (sj <= ti && ss <= tt) ? f2bf(a[r]) : (bf16_t)0; }
;             }
; #pragma unroll
;             for (int ti = 0; ti < 4; ++ti) { o[ti] = (f32x4){0.f, 0.f, 0.f, 0.f};
; #pragma unroll
;                 for (int ks = 0; ks < 4; ++ks) { const LAS bf16_t* qp = Qt + (16 * ti + e16) * QP + 32 * ks + 4 * rq; const u32x2 q0 = *(const LAS u32x2*)qp, q1 = *(const LAS u32x2*)(qp + 16);
;                     u32x4 qa = {q0.x, q0.y, q1.x, q1.y};
;                     u32x4 sb; sb.x = pk2(st[2 * ks][0], st[2 * ks][1]); sb.y = pk2(st[2 * ks][2], st[2 * ks][3]); sb.z = pk2(st[2 * ks + 1][0], st[2 * ks + 1][1]); sb.w = pk2(st[2 * ks + 1][2], st[2 * ks + 1][3]);
;                     o[ti] = MFMA16(__builtin_bit_cast(bf16x8, qa), __builtin_bit_cast(bf16x8, sb), o[ti]); } }
;         }
; #pragma unroll
;         for (int dt = 0; dt < 8; ++dt) {
; #pragma unroll
;             for (int ks = 0; ks < 2; ++ks) { const bf16x8 ka = *(const LAS bf16x8*)(KtT + (16 * dt + e16) * TP + 32 * ks + 8 * rq); st[dt] = MFMA16(ka, vfr[ks], st[dt]); }
;             const f32x4 dv = *(const LAS f32x4*)(Dv + 16 * dt + 4 * rq);
;             st[dt] *= dv;
;         }
	ds_read_b128 v[80:83], v69 offset:34816
	ds_read_b128 v[84:87], v69 offset:34880
	ds_read_b128 v[88:91], v71 offset:53248
	ds_read_b128 v[92:95], v71 offset:53312
	s_waitcnt lgkmcnt(1)
	v_mfma_f32_16x16x32_bf16 v[30:33], v[80:83], v[88:91], v[30:33]
	ds_read_b128 v[80:83], v69 offset:37120
	v_add_u32_e32 v104, 0x13c00, v66
	s_waitcnt lgkmcnt(1)
	v_mfma_f32_16x16x32_bf16 v[30:33], v[84:87], v[92:95], v[30:33]
	ds_read_b128 v[84:87], v69 offset:37184
	s_waitcnt lgkmcnt(1)
	v_mfma_f32_16x16x32_bf16 v[26:29], v[80:83], v[88:91], v[26:29]
	ds_read_b128 v[80:83], v69 offset:39424
	s_waitcnt lgkmcnt(1)
	v_mfma_f32_16x16x32_bf16 v[26:29], v[84:87], v[92:95], v[26:29]
	ds_read_b128 v[84:87], v69 offset:39488
	ds_read_b128 v[96:99], v69 offset:41728
	s_waitcnt lgkmcnt(2)
	v_mfma_f32_16x16x32_bf16 v[22:25], v[80:83], v[88:91], v[22:25]
	ds_read_b128 v[80:83], v104
	ds_read_b128 v[100:103], v69 offset:41792
	s_waitcnt lgkmcnt(1)
	v_pk_mul_f32 v[32:33], v[32:33], v[82:83]
	v_mfma_f32_16x16x32_bf16 v[22:25], v[84:87], v[92:95], v[22:25]
	ds_read_b128 v[58:61], v104 offset:64
	ds_read_b128 v[84:87], v69 offset:44032
	v_pk_mul_f32 v[30:31], v[30:31], v[80:81]
	ds_read_b128 v[80:83], v69 offset:44096
	v_mfma_f32_16x16x32_bf16 v[18:21], v[96:99], v[88:91], v[18:21]
	s_waitcnt lgkmcnt(2)
	v_pk_mul_f32 v[28:29], v[28:29], v[60:61]
	v_pk_mul_f32 v[26:27], v[26:27], v[58:59]
	s_waitcnt lgkmcnt(1)
	v_mfma_f32_16x16x32_bf16 v[14:17], v[84:87], v[88:91], v[14:17]
	v_mfma_f32_16x16x32_bf16 v[18:21], v[100:103], v[92:95], v[18:21]
	ds_read_b128 v[96:99], v104 offset:128
	ds_read_b128 v[100:103], v69 offset:46336
	ds_read_b128 v[58:61], v104 offset:192
	ds_read_b128 v[84:87], v69 offset:46400
	s_waitcnt lgkmcnt(3)
	v_pk_mul_f32 v[24:25], v[24:25], v[98:99]
	v_mfma_f32_16x16x32_bf16 v[14:17], v[80:83], v[92:95], v[14:17]
	ds_read_b128 v[80:83], v69 offset:48640
	v_pk_mul_f32 v[22:23], v[22:23], v[96:97]
	s_waitcnt lgkmcnt(2)
	v_pk_mul_f32 v[20:21], v[20:21], v[60:61]
	v_mfma_f32_16x16x32_bf16 v[10:13], v[100:103], v[88:91], v[10:13]
	ds_read_b128 v[96:99], v104 offset:256
	ds_read_b128 v[100:103], v69 offset:48704
	v_pk_mul_f32 v[18:19], v[18:19], v[58:59]
	s_waitcnt lgkmcnt(1)
	v_pk_mul_f32 v[16:17], v[16:17], v[98:99]
	v_mfma_f32_16x16x32_bf16 v[10:13], v[84:87], v[92:95], v[10:13]
	ds_read_b128 v[58:61], v104 offset:320
	ds_read_b128 v[84:87], v69 offset:50944
	v_pk_mul_f32 v[14:15], v[14:15], v[96:97]
	ds_read_b128 v[96:99], v104 offset:384
	v_mfma_f32_16x16x32_bf16 v[2:5], v[80:83], v[88:91], v[2:5]
	ds_read_b128 v[80:83], v69 offset:51008
	s_waitcnt lgkmcnt(3)
	s_nop 0
	v_pk_mul_f32 v[12:13], v[12:13], v[60:61]
	v_pk_mul_f32 v[10:11], v[10:11], v[58:59]
	s_waitcnt lgkmcnt(2)
	v_mfma_f32_16x16x32_bf16 v[6:9], v[84:87], v[88:91], v[6:9]
	ds_read_b128 v[58:61], v104 offset:448
	s_waitcnt lgkmcnt(0)
	s_barrier
	v_mfma_f32_16x16x32_bf16 v[2:5], v[100:103], v[92:95], v[2:5]
	v_mfma_f32_16x16x32_bf16 v[6:9], v[80:83], v[92:95], v[6:9]
	s_nop 6
	v_mul_f32_e64 v4, v4, v98
	v_mul_f32_e64 v5, v5, v99
	v_pk_mul_f32 v[2:3], v[2:3], v[96:97]
	v_pk_mul_f32 v[8:9], v[8:9], v[60:61]
	v_pk_mul_f32 v[6:7], v[6:7], v[58:59]
	s_cbranch_scc1 .LBB0_831
	s_waitcnt vmcnt(0)
	v_lshl_or_b32 v72, v131, 16, v130
	v_lshl_or_b32 v73, v134, 16, v133
	v_lshl_or_b32 v74, v139, 16, v138
	v_lshl_or_b32 v75, v142, 16, v141
	v_lshl_or_b32 v34, v132, 16, v137
	v_lshl_or_b32 v35, v136, 16, v135
	v_lshl_or_b32 v36, v140, 16, v145
	v_lshl_or_b32 v37, v143, 16, v144
	v_lshl_or_b32 v76, v147, 16, v146
	v_lshl_or_b32 v39, v152, 16, v151
	v_lshl_or_b32 v38, v148, 16, v153
	v_lshl_or_b32 v77, v150, 16, v149
	v_lshl_or_b32 v78, v155, 16, v154
	v_lshl_or_b32 v41, v158, 16, v159
	v_lshl_or_b32 v40, v156, 16, v160
	v_lshl_or_b32 v79, v161, 16, v157
	v_mov_b32_e32 v58, v72
	v_mov_b32_e32 v59, v73
	v_mov_b32_e32 v60, v74
	v_mov_b32_e32 v61, v75
	v_mov_b32_e32 v80, v76
	v_mov_b32_e32 v81, v77
	v_mov_b32_e32 v82, v78
	v_mov_b32_e32 v83, v79
	s_cmp_eq_u32 s36, 0x258000
	ds_write_b128 v63, v[34:37] offset:53248
	ds_write_b128 v63, v[38:41] offset:53264
	s_cbranch_scc0 .LBB0_826
	s_branch .LBB0_827
